# P4 epilogue: row scale r computed for 2 rows per lane and shared across the 4 fq lane groups through LDS (was 8 identical IEEE sqrt+div chains per lane)
# baseline (speedup 1.0000x reference)
; #define PG8_STAGE(bufoff, gbase, voff) do { _Pragma("unroll") for (int _i = 0; _i < 2; ++_i) \
;         __builtin_amdgcn_global_load_lds((const unsigned*)((const char*)(gbase) + (voff)[_i]), (PG8_LAS unsigned*)(lds + (bufoff) + ldsw + _i * 8192), 16, 0, 0); } while (0)
; #define PG8_LDA(dst, b, h) do { _Pragma("unroll") for (int m = 0; m < 4; ++m) _Pragma("unroll") for (int k = 0; k < 2; ++k) dst[m][k] = *(const PG8_LAS bf16x8*)(lds + PG8_SA(b, h) + aoff + m * 2048 + k * 1024); } while (0)
; #define PG8_LDB(dst, b, h) do { _Pragma("unroll") for (int n = 0; n < 2; ++n) _Pragma("unroll") for (int k = 0; k < 2; ++k) dst[n][k] = *(const PG8_LAS bf16x8*)(lds + PG8_SB(b, h) + boff + n * 2048 + k * 1024); } while (0)
; #define PG8_MMA(ai, bj, At, Bt) do { __builtin_amdgcn_s_setprio(1); _Pragma("unroll") for (int m = 0; m < 4; ++m) _Pragma("unroll") for (int n = 0; n < 2; ++n) _Pragma("unroll") for (int k = 0; k < 2; ++k) \
;         acc[ai][bj][m][n] = __builtin_amdgcn_mfma_f32_16x16x32_bf16(Bt[n][k], At[m][k], acc[ai][bj][m][n], 0, 0, 0); __builtin_amdgcn_s_setprio(0); } while (0)
; #define PG8_WAIT_V(n) asm volatile("s_waitcnt vmcnt(" #n ")" ::: "memory")
; #define PG8_WAIT_L(n) asm volatile("s_waitcnt lgkmcnt(" #n ")" ::: "memory")
; #define PG8_BAR __builtin_amdgcn_s_barrier()
; #define PG8_SCHED __builtin_amdgcn_sched_barrier(0)
; template <class Epi, class Sched, bool ALIGN_EPI = false, bool SP2 = false>
; __device__ __forceinline__ void gemm_phase(PG8_LAS unsigned char* lds, const Gemm g, const Sched& S, const Epi& E) {
;     ...
;             PG8_LDB(B0, 0, 0); PG8_LDB(B1, 0, 1); PG8_SCHED; PG8_LDA(At, 0, 0); PG8_STAGE(PG8_SA(1, 1), a1 + hstep, voffA);
;             PG8_WAIT_V(8); PG8_WAIT_L(0); PG8_BAR; PG8_MMA(0, 0, At, B0); PG8_MMA(0, 1, At, B1); PG8_BAR; PG8_SCHED;
;             PG8_LDA(At, 0, 1); PG8_STAGE(PG8_SB(0, 0), b2, voffB); PG8_STAGE(PG8_SB(0, 1), b2 + hstep, voffB); PG8_STAGE(PG8_SA(0, 0), a2, voffA);
;             PG8_WAIT_V(8); PG8_WAIT_L(0); PG8_BAR; PG8_MMA(1, 0, At, B0); PG8_MMA(1, 1, At, B1); PG8_BAR; PG8_SCHED;
.LBB0_981:
	ds_read_b128 v[138:141], v144
	ds_read_b128 v[150:153], v144 offset:1024
	ds_read_b128 v[154:157], v144 offset:2048
	ds_read_b128 v[158:161], v144 offset:3072
	ds_read_b128 v[162:165], v145
	ds_read_b128 v[166:169], v145 offset:1024
	ds_read_b128 v[170:173], v145 offset:2048
	ds_read_b128 v[174:177], v145 offset:3072
	s_add_u32 s51, s12, 0xfffc4000
	s_addc_u32 s67, s13, -1
	s_cmp_eq_u32 s50, 12
	s_cselect_b32 s69, s39, s67
	s_cselect_b32 s68, s48, s51
	s_cselect_b32 s71, s37, s45
	s_cselect_b32 s70, s49, s44
	v_lshl_add_u64 v[198:199], s[12:13], 0, v[130:131]
	s_add_i32 m0, s47, 0xc000
	ds_read_b128 v[178:181], v146
	ds_read_b128 v[182:185], v146 offset:1024
	ds_read_b128 v[186:189], v146 offset:2048
	ds_read_b128 v[190:193], v146 offset:3072
	ds_read_b128 v[194:197], v146 offset:4096
	ds_read_b128 v[202:205], v146 offset:5120
	ds_read_b128 v[206:209], v146 offset:6144
	ds_read_b128 v[210:213], v146 offset:7168
	global_load_lds_dwordx4 v[198:199], off
	v_lshl_add_u64 v[198:199], v[198:199], 0, s[6:7]
	s_add_i32 m0, s47, 0xe000
	s_nop 0
	global_load_lds_dwordx4 v[198:199], off
	s_waitcnt vmcnt(8)
	s_waitcnt lgkmcnt(0)
	s_barrier
	s_setprio 1
	s_waitcnt lgkmcnt(0)
	v_mfma_f32_16x16x32_bf16 v[118:121], v[138:141], v[178:181], v[118:121]
	v_mfma_f32_16x16x32_bf16 v[114:117], v[154:157], v[178:181], v[114:117]
	v_mfma_f32_16x16x32_bf16 v[102:105], v[138:141], v[186:189], v[102:105]
	v_mfma_f32_16x16x32_bf16 v[98:101], v[154:157], v[186:189], v[98:101]
	v_mfma_f32_16x16x32_bf16 v[86:89], v[138:141], v[194:197], v[86:89]
	v_mfma_f32_16x16x32_bf16 v[82:85], v[154:157], v[194:197], v[82:85]
	v_mfma_f32_16x16x32_bf16 v[70:73], v[138:141], v[206:209], v[70:73]
	v_mfma_f32_16x16x32_bf16 v[66:69], v[154:157], v[206:209], v[66:69]
	v_mfma_f32_16x16x32_bf16 v[118:121], v[150:153], v[182:185], v[118:121]
	v_mfma_f32_16x16x32_bf16 v[114:117], v[158:161], v[182:185], v[114:117]
	v_mfma_f32_16x16x32_bf16 v[102:105], v[150:153], v[190:193], v[102:105]
	v_mfma_f32_16x16x32_bf16 v[98:101], v[158:161], v[190:193], v[98:101]
	v_mfma_f32_16x16x32_bf16 v[86:89], v[150:153], v[202:205], v[86:89]
	v_mfma_f32_16x16x32_bf16 v[82:85], v[158:161], v[202:205], v[82:85]
	v_mfma_f32_16x16x32_bf16 v[70:73], v[150:153], v[210:213], v[70:73]
	v_mfma_f32_16x16x32_bf16 v[66:69], v[158:161], v[210:213], v[66:69]
	s_setprio 0
	s_setprio 1
	v_mfma_f32_16x16x32_bf16 v[126:129], v[162:165], v[178:181], v[126:129]
	v_mfma_f32_16x16x32_bf16 v[122:125], v[170:173], v[178:181], v[122:125]
	v_mfma_f32_16x16x32_bf16 v[110:113], v[162:165], v[186:189], v[110:113]
	v_mfma_f32_16x16x32_bf16 v[106:109], v[170:173], v[186:189], v[106:109]
	v_mfma_f32_16x16x32_bf16 v[94:97], v[162:165], v[194:197], v[94:97]
	v_mfma_f32_16x16x32_bf16 v[90:93], v[170:173], v[194:197], v[90:93]
	v_mfma_f32_16x16x32_bf16 v[78:81], v[162:165], v[206:209], v[78:81]
	v_mfma_f32_16x16x32_bf16 v[74:77], v[170:173], v[206:209], v[74:77]
	v_mfma_f32_16x16x32_bf16 v[126:129], v[166:169], v[182:185], v[126:129]
	v_mfma_f32_16x16x32_bf16 v[122:125], v[174:177], v[182:185], v[122:125]
	v_mfma_f32_16x16x32_bf16 v[110:113], v[166:169], v[190:193], v[110:113]
	v_mfma_f32_16x16x32_bf16 v[106:109], v[174:177], v[190:193], v[106:109]
	v_mfma_f32_16x16x32_bf16 v[94:97], v[166:169], v[202:205], v[94:97]
	v_mfma_f32_16x16x32_bf16 v[90:93], v[174:177], v[202:205], v[90:93]
	v_mfma_f32_16x16x32_bf16 v[78:81], v[166:169], v[210:213], v[78:81]
	v_mfma_f32_16x16x32_bf16 v[74:77], v[174:177], v[210:213], v[74:77]
	s_setprio 0
	s_barrier
	s_add_i32 s51, s64, s46
	v_lshl_add_u64 v[198:199], s[70:71], 0, v[130:131]
	s_mov_b32 m0, s51
	ds_read_b128 v[178:181], v146 offset:16384
	ds_read_b128 v[182:185], v146 offset:17408
	ds_read_b128 v[186:189], v146 offset:18432
	ds_read_b128 v[190:193], v146 offset:19456
	ds_read_b128 v[194:197], v146 offset:20480
	ds_read_b128 v[202:205], v146 offset:21504
	ds_read_b128 v[206:209], v146 offset:22528
	ds_read_b128 v[210:213], v146 offset:23552
	global_load_lds_dwordx4 v[198:199], off
	v_lshl_add_u64 v[214:215], v[198:199], 0, s[6:7]
	s_add_i32 m0, s51, 0x2000
	s_add_i32 s51, s65, s46
	global_load_lds_dwordx4 v[214:215], off
	v_lshl_add_u64 v[214:215], v[198:199], 0, s[10:11]
	s_mov_b32 m0, s51
	s_nop 0
	global_load_lds_dwordx4 v[214:215], off
	v_lshl_add_u64 v[214:215], v[198:199], 0, s[14:15]
	s_add_i32 m0, s51, 0x2000
	s_nop 0
	global_load_lds_dwordx4 v[214:215], off
	v_lshl_add_u64 v[214:215], s[68:69], 0, v[130:131]
	s_mov_b32 m0, s47
	v_lshl_add_u64 v[216:217], v[214:215], 0, s[6:7]
	global_load_lds_dwordx4 v[214:215], off
	s_mov_b32 m0, s52
	s_nop 0
	global_load_lds_dwordx4 v[216:217], off
	s_waitcnt vmcnt(8)
	s_waitcnt lgkmcnt(0)
	s_barrier
; #define PG8_STAGE(bufoff, gbase, voff) do { _Pragma("unroll") for (int _i = 0; _i < 2; ++_i) \
;         __builtin_amdgcn_global_load_lds((const unsigned*)((const char*)(gbase) + (voff)[_i]), (PG8_LAS unsigned*)(lds + (bufoff) + ldsw + _i * 8192), 16, 0, 0); } while (0)
; #define PG8_LDA(dst, b, h) do { _Pragma("unroll") for (int m = 0; m < 4; ++m) _Pragma("unroll") for (int k = 0; k < 2; ++k) dst[m][k] = *(const PG8_LAS bf16x8*)(lds + PG8_SA(b, h) + aoff + m * 2048 + k * 1024); } while (0)
; #define PG8_LDB(dst, b, h) do { _Pragma("unroll") for (int n = 0; n < 2; ++n) _Pragma("unroll") for (int k = 0; k < 2; ++k) dst[n][k] = *(const PG8_LAS bf16x8*)(lds + PG8_SB(b, h) + boff + n * 2048 + k * 1024); } while (0)
; #define PG8_MMA(ai, bj, At, Bt) do { __builtin_amdgcn_s_setprio(1); _Pragma("unroll") for (int m = 0; m < 4; ++m) _Pragma("unroll") for (int n = 0; n < 2; ++n) _Pragma("unroll") for (int k = 0; k < 2; ++k) \
;         acc[ai][bj][m][n] = __builtin_amdgcn_mfma_f32_16x16x32_bf16(Bt[n][k], At[m][k], acc[ai][bj][m][n], 0, 0, 0); __builtin_amdgcn_s_setprio(0); } while (0)
; #define PG8_WAIT_V(n) asm volatile("s_waitcnt vmcnt(" #n ")" ::: "memory")
; #define PG8_WAIT_L(n) asm volatile("s_waitcnt lgkmcnt(" #n ")" ::: "memory")
; #define PG8_BAR __builtin_amdgcn_s_barrier()
; #define PG8_SCHED __builtin_amdgcn_sched_barrier(0)
; template <class Epi, class Sched, bool ALIGN_EPI = false, bool SP2 = false>
; __device__ __forceinline__ void gemm_phase(PG8_LAS unsigned char* lds, const Gemm g, const Sched& S, const Epi& E) {
;     ...
;             PG8_WAIT_V(8); PG8_WAIT_L(0); PG8_BAR; PG8_MMA(1, 0, At, B0); PG8_MMA(1, 1, At, B1); PG8_BAR; PG8_SCHED;
;             PG8_LDB(B0, 1, 0); PG8_LDB(B1, 1, 1); PG8_SCHED; PG8_LDA(At, 1, 0); PG8_STAGE(PG8_SA(0, 1), a2 + hstep, voffA);
;             PG8_WAIT_V(8); PG8_WAIT_L(0); PG8_BAR; PG8_MMA(0, 0, At, B0); PG8_MMA(0, 1, At, B1); PG8_BAR; PG8_SCHED;
	s_setprio 1
	s_waitcnt lgkmcnt(0)
	v_mfma_f32_16x16x32_bf16 v[54:57], v[138:141], v[178:181], v[54:57]
	v_mfma_f32_16x16x32_bf16 v[50:53], v[154:157], v[178:181], v[50:53]
	v_mfma_f32_16x16x32_bf16 v[38:41], v[138:141], v[186:189], v[38:41]
	v_mfma_f32_16x16x32_bf16 v[34:37], v[154:157], v[186:189], v[34:37]
	v_mfma_f32_16x16x32_bf16 v[22:25], v[138:141], v[194:197], v[22:25]
	v_mfma_f32_16x16x32_bf16 v[18:21], v[154:157], v[194:197], v[18:21]
	v_mfma_f32_16x16x32_bf16 v[6:9], v[138:141], v[206:209], v[6:9]
	v_mfma_f32_16x16x32_bf16 v[2:5], v[154:157], v[206:209], v[2:5]
	v_mfma_f32_16x16x32_bf16 v[54:57], v[150:153], v[182:185], v[54:57]
	v_mfma_f32_16x16x32_bf16 v[50:53], v[158:161], v[182:185], v[50:53]
	v_mfma_f32_16x16x32_bf16 v[38:41], v[150:153], v[190:193], v[38:41]
	v_mfma_f32_16x16x32_bf16 v[34:37], v[158:161], v[190:193], v[34:37]
	v_mfma_f32_16x16x32_bf16 v[22:25], v[150:153], v[202:205], v[22:25]
	v_mfma_f32_16x16x32_bf16 v[18:21], v[158:161], v[202:205], v[18:21]
	v_mfma_f32_16x16x32_bf16 v[6:9], v[150:153], v[210:213], v[6:9]
	v_mfma_f32_16x16x32_bf16 v[2:5], v[158:161], v[210:213], v[2:5]
	s_setprio 0
	s_setprio 1
	v_mfma_f32_16x16x32_bf16 v[62:65], v[162:165], v[178:181], v[62:65]
	v_mfma_f32_16x16x32_bf16 v[58:61], v[170:173], v[178:181], v[58:61]
	v_mfma_f32_16x16x32_bf16 v[46:49], v[162:165], v[186:189], v[46:49]
	v_mfma_f32_16x16x32_bf16 v[42:45], v[170:173], v[186:189], v[42:45]
	v_mfma_f32_16x16x32_bf16 v[30:33], v[162:165], v[194:197], v[30:33]
	v_mfma_f32_16x16x32_bf16 v[26:29], v[170:173], v[194:197], v[26:29]
	v_mfma_f32_16x16x32_bf16 v[14:17], v[162:165], v[206:209], v[14:17]
	v_mfma_f32_16x16x32_bf16 v[10:13], v[170:173], v[206:209], v[10:13]
	v_mfma_f32_16x16x32_bf16 v[62:65], v[166:169], v[182:185], v[62:65]
	v_mfma_f32_16x16x32_bf16 v[58:61], v[174:177], v[182:185], v[58:61]
	v_mfma_f32_16x16x32_bf16 v[46:49], v[166:169], v[190:193], v[46:49]
	v_mfma_f32_16x16x32_bf16 v[42:45], v[174:177], v[190:193], v[42:45]
	v_mfma_f32_16x16x32_bf16 v[30:33], v[166:169], v[202:205], v[30:33]
	v_mfma_f32_16x16x32_bf16 v[26:29], v[174:177], v[202:205], v[26:29]
	v_mfma_f32_16x16x32_bf16 v[14:17], v[166:169], v[210:213], v[14:17]
	v_mfma_f32_16x16x32_bf16 v[10:13], v[174:177], v[210:213], v[10:13]
	s_setprio 0
	s_barrier
	s_add_i32 s51, 0, 0x18000
	v_add_u32_e32 v132, s51, v143
	s_add_i32 s67, 0, 0x1c000
	ds_read_b128 v[138:141], v132
	ds_read_b128 v[150:153], v132 offset:1024
	ds_read_b128 v[154:157], v132 offset:2048
	ds_read_b128 v[158:161], v132 offset:3072
	v_add_u32_e32 v132, s67, v143
	ds_read_b128 v[162:165], v132
	ds_read_b128 v[166:169], v132 offset:1024
	ds_read_b128 v[170:173], v132 offset:2048
	ds_read_b128 v[174:177], v132 offset:3072
	s_mov_b32 m0, s53
	v_lshl_add_u64 v[216:217], v[214:215], 0, s[10:11]
	ds_read_b128 v[178:181], v146 offset:32768
	ds_read_b128 v[182:185], v146 offset:33792
	ds_read_b128 v[186:189], v146 offset:34816
	ds_read_b128 v[190:193], v146 offset:35840
	ds_read_b128 v[194:197], v146 offset:36864
	ds_read_b128 v[202:205], v146 offset:37888
	ds_read_b128 v[206:209], v146 offset:38912
	ds_read_b128 v[210:213], v146 offset:39936
	global_load_lds_dwordx4 v[216:217], off
	v_lshl_add_u64 v[216:217], v[214:215], 0, s[14:15]
	s_mov_b32 m0, s54
	s_nop 0
	global_load_lds_dwordx4 v[216:217], off
	s_waitcnt vmcnt(8)
	s_waitcnt lgkmcnt(0)
	s_barrier
	s_setprio 1
	s_waitcnt lgkmcnt(0)
	v_mfma_f32_16x16x32_bf16 v[118:121], v[138:141], v[178:181], v[118:121]
	v_mfma_f32_16x16x32_bf16 v[114:117], v[154:157], v[178:181], v[114:117]
	v_mfma_f32_16x16x32_bf16 v[102:105], v[138:141], v[186:189], v[102:105]
	v_mfma_f32_16x16x32_bf16 v[98:101], v[154:157], v[186:189], v[98:101]
	v_mfma_f32_16x16x32_bf16 v[86:89], v[138:141], v[194:197], v[86:89]
	v_mfma_f32_16x16x32_bf16 v[82:85], v[154:157], v[194:197], v[82:85]
	v_mfma_f32_16x16x32_bf16 v[70:73], v[138:141], v[206:209], v[70:73]
	v_mfma_f32_16x16x32_bf16 v[66:69], v[154:157], v[206:209], v[66:69]
	v_mfma_f32_16x16x32_bf16 v[118:121], v[150:153], v[182:185], v[118:121]
	v_mfma_f32_16x16x32_bf16 v[114:117], v[158:161], v[182:185], v[114:117]
	v_mfma_f32_16x16x32_bf16 v[102:105], v[150:153], v[190:193], v[102:105]
	v_mfma_f32_16x16x32_bf16 v[98:101], v[158:161], v[190:193], v[98:101]
	v_mfma_f32_16x16x32_bf16 v[86:89], v[150:153], v[202:205], v[86:89]
	v_mfma_f32_16x16x32_bf16 v[82:85], v[158:161], v[202:205], v[82:85]
	v_mfma_f32_16x16x32_bf16 v[70:73], v[150:153], v[210:213], v[70:73]
	v_mfma_f32_16x16x32_bf16 v[66:69], v[158:161], v[210:213], v[66:69]
	s_setprio 0
	s_setprio 1
	v_mfma_f32_16x16x32_bf16 v[126:129], v[162:165], v[178:181], v[126:129]
	v_mfma_f32_16x16x32_bf16 v[122:125], v[170:173], v[178:181], v[122:125]
	v_mfma_f32_16x16x32_bf16 v[110:113], v[162:165], v[186:189], v[110:113]
	v_mfma_f32_16x16x32_bf16 v[106:109], v[170:173], v[186:189], v[106:109]
	v_mfma_f32_16x16x32_bf16 v[94:97], v[162:165], v[194:197], v[94:97]
	v_mfma_f32_16x16x32_bf16 v[90:93], v[170:173], v[194:197], v[90:93]
	v_mfma_f32_16x16x32_bf16 v[78:81], v[162:165], v[206:209], v[78:81]
	v_mfma_f32_16x16x32_bf16 v[74:77], v[170:173], v[206:209], v[74:77]
	v_mfma_f32_16x16x32_bf16 v[126:129], v[166:169], v[182:185], v[126:129]
	v_mfma_f32_16x16x32_bf16 v[122:125], v[174:177], v[182:185], v[122:125]
	v_mfma_f32_16x16x32_bf16 v[110:113], v[166:169], v[190:193], v[110:113]
	v_mfma_f32_16x16x32_bf16 v[106:109], v[174:177], v[190:193], v[106:109]
	v_mfma_f32_16x16x32_bf16 v[94:97], v[166:169], v[202:205], v[94:97]
	v_mfma_f32_16x16x32_bf16 v[90:93], v[174:177], v[202:205], v[90:93]
	v_mfma_f32_16x16x32_bf16 v[78:81], v[166:169], v[210:213], v[78:81]
	v_mfma_f32_16x16x32_bf16 v[74:77], v[174:177], v[210:213], v[74:77]
	s_setprio 0
	s_barrier
; #define PG8_STAGE(bufoff, gbase, voff) do { _Pragma("unroll") for (int _i = 0; _i < 2; ++_i) \
;         __builtin_amdgcn_global_load_lds((const unsigned*)((const char*)(gbase) + (voff)[_i]), (PG8_LAS unsigned*)(lds + (bufoff) + ldsw + _i * 8192), 16, 0, 0); } while (0)
; #define PG8_WAIT_V(n) asm volatile("s_waitcnt vmcnt(" #n ")" ::: "memory")
;     __device__ __forceinline__ void operator()(const f32x4 (&acc)[2][2][4][2], const Unit& u, int wr, int wc, int fr, int fq) const {
;     ...
;             for (int m = 0; m < 4; ++m) { const int row = row0 + ai * HALF + m * 16;
;                 const float r = 1.0f / sqrtf(__hip_atomic_load(ss + row, __ATOMIC_RELAXED, __HIP_MEMORY_SCOPE_AGENT) * (1.0f / 1024.0f) + 1e-6f);
; template <class Epi, class Sched, bool ALIGN_EPI = false, bool SP2 = false>
; __device__ __forceinline__ void gemm_phase(PG8_LAS unsigned char* lds, const Gemm g, const Sched& S, const Epi& E) {
;     ...
;         for (int t = 0; t < nt; t += 2) {
;             const bool last = (t == nt - 2);
;             const char* a1 = cA + (size_t)(t + 1) * kstep;
;             const char* a2 = last ? nA : cA + (size_t)(t + 2) * kstep; const char* b2 = last ? nB : cB + (size_t)(t + 2) * kstep;
;             const char* a3 = a2 + kstep; const char* b3 = b2 + kstep;
;             if (last && has_next) S.a_ready(nxt);
;             if constexpr (SP2) {
;             PG8_LDB(B0, 0, 0); PG8_LDB(B1, 0, 1); PG8_SCHED; PG8_LDA(At, 0, 0); PG8_STAGE(PG8_SA(1, 1), a1 + hstep, voffA);
;             PG8_WAIT_V(8); PG8_WAIT_L(0); PG8_BAR; PG8_MMA(0, 0, At, B0); PG8_MMA(0, 1, At, B1); PG8_BAR; PG8_SCHED;
;             PG8_LDA(At, 0, 1); PG8_STAGE(PG8_SB(0, 0), b2, voffB); PG8_STAGE(PG8_SB(0, 1), b2 + hstep, voffB); PG8_STAGE(PG8_SA(0, 0), a2, voffA);
;             PG8_WAIT_V(8); PG8_WAIT_L(0); PG8_BAR; PG8_MMA(1, 0, At, B0); PG8_MMA(1, 1, At, B1); PG8_BAR; PG8_SCHED;
;             PG8_LDB(B0, 1, 0); PG8_LDB(B1, 1, 1); PG8_SCHED; PG8_LDA(At, 1, 0); PG8_STAGE(PG8_SA(0, 1), a2 + hstep, voffA);
;             PG8_WAIT_V(8); PG8_WAIT_L(0); PG8_BAR; PG8_MMA(0, 0, At, B0); PG8_MMA(0, 1, At, B1); PG8_BAR; PG8_SCHED;
;             PG8_LDA(At, 1, 1); PG8_STAGE(PG8_SB(1, 0), b3, voffB); PG8_STAGE(PG8_SB(1, 1), b3 + hstep, voffB); PG8_STAGE(PG8_SA(1, 0), a3, voffA);
;             PG8_WAIT_V(8); PG8_WAIT_L(0); PG8_BAR; PG8_MMA(1, 0, At, B0); PG8_MMA(1, 1, At, B1); PG8_BAR; PG8_SCHED;
	s_add_i32 s51, s51, s46
	v_lshl_add_u64 v[216:217], v[198:199], 0, s[18:19]
	s_mov_b32 m0, s51
	ds_read_b128 v[178:181], v146 offset:49152
	ds_read_b128 v[182:185], v146 offset:50176
	ds_read_b128 v[186:189], v146 offset:51200
	ds_read_b128 v[190:193], v146 offset:52224
	ds_read_b128 v[194:197], v146 offset:53248
	ds_read_b128 v[202:205], v146 offset:54272
	ds_read_b128 v[206:209], v146 offset:55296
	ds_read_b128 v[210:213], v146 offset:56320
	global_load_lds_dwordx4 v[216:217], off
	v_lshl_add_u64 v[216:217], v[198:199], 0, s[20:21]
	s_add_i32 m0, s51, 0x2000
	s_add_i32 s51, s67, s46
	global_load_lds_dwordx4 v[216:217], off
	v_lshl_add_u64 v[216:217], v[198:199], 0, s[22:23]
	s_mov_b32 m0, s51
	v_lshl_add_u64 v[198:199], v[198:199], 0, s[24:25]
	global_load_lds_dwordx4 v[216:217], off
	s_add_i32 m0, s51, 0x2000
	s_nop 0
	global_load_lds_dwordx4 v[198:199], off
	v_lshl_add_u64 v[198:199], v[214:215], 0, s[18:19]
	s_mov_b32 m0, s56
	s_nop 0
	global_load_lds_dwordx4 v[198:199], off
	v_lshl_add_u64 v[198:199], v[214:215], 0, s[20:21]
	s_mov_b32 m0, s57
	s_nop 0
	global_load_lds_dwordx4 v[198:199], off
	s_waitcnt vmcnt(8)
	s_waitcnt lgkmcnt(0)
	s_barrier
	s_setprio 1
	s_waitcnt lgkmcnt(0)
	v_mfma_f32_16x16x32_bf16 v[54:57], v[138:141], v[178:181], v[54:57]
	v_mfma_f32_16x16x32_bf16 v[50:53], v[154:157], v[178:181], v[50:53]
	v_mfma_f32_16x16x32_bf16 v[38:41], v[138:141], v[186:189], v[38:41]
	v_mfma_f32_16x16x32_bf16 v[34:37], v[154:157], v[186:189], v[34:37]
	v_mfma_f32_16x16x32_bf16 v[22:25], v[138:141], v[194:197], v[22:25]
	v_mfma_f32_16x16x32_bf16 v[18:21], v[154:157], v[194:197], v[18:21]
	v_mfma_f32_16x16x32_bf16 v[6:9], v[138:141], v[206:209], v[6:9]
	v_mfma_f32_16x16x32_bf16 v[2:5], v[154:157], v[206:209], v[2:5]
	v_mfma_f32_16x16x32_bf16 v[54:57], v[150:153], v[182:185], v[54:57]
	v_mfma_f32_16x16x32_bf16 v[50:53], v[158:161], v[182:185], v[50:53]
	v_mfma_f32_16x16x32_bf16 v[38:41], v[150:153], v[190:193], v[38:41]
	v_mfma_f32_16x16x32_bf16 v[34:37], v[158:161], v[190:193], v[34:37]
	v_mfma_f32_16x16x32_bf16 v[22:25], v[150:153], v[202:205], v[22:25]
	v_mfma_f32_16x16x32_bf16 v[18:21], v[158:161], v[202:205], v[18:21]
	v_mfma_f32_16x16x32_bf16 v[6:9], v[150:153], v[210:213], v[6:9]
	v_mfma_f32_16x16x32_bf16 v[2:5], v[158:161], v[210:213], v[2:5]
	s_setprio 0
	s_setprio 1
	v_mfma_f32_16x16x32_bf16 v[62:65], v[162:165], v[178:181], v[62:65]
	v_mfma_f32_16x16x32_bf16 v[58:61], v[170:173], v[178:181], v[58:61]
	v_mfma_f32_16x16x32_bf16 v[46:49], v[162:165], v[186:189], v[46:49]
	v_mfma_f32_16x16x32_bf16 v[42:45], v[170:173], v[186:189], v[42:45]
	v_mfma_f32_16x16x32_bf16 v[30:33], v[162:165], v[194:197], v[30:33]
	v_mfma_f32_16x16x32_bf16 v[26:29], v[170:173], v[194:197], v[26:29]
	v_mfma_f32_16x16x32_bf16 v[14:17], v[162:165], v[206:209], v[14:17]
	v_mfma_f32_16x16x32_bf16 v[10:13], v[170:173], v[206:209], v[10:13]
	v_mfma_f32_16x16x32_bf16 v[62:65], v[166:169], v[182:185], v[62:65]
	v_mfma_f32_16x16x32_bf16 v[58:61], v[174:177], v[182:185], v[58:61]
	v_mfma_f32_16x16x32_bf16 v[46:49], v[166:169], v[190:193], v[46:49]
	v_mfma_f32_16x16x32_bf16 v[42:45], v[174:177], v[190:193], v[42:45]
	v_mfma_f32_16x16x32_bf16 v[30:33], v[166:169], v[202:205], v[30:33]
	v_mfma_f32_16x16x32_bf16 v[26:29], v[174:177], v[202:205], v[26:29]
	v_mfma_f32_16x16x32_bf16 v[14:17], v[166:169], v[210:213], v[14:17]
	v_mfma_f32_16x16x32_bf16 v[10:13], v[174:177], v[210:213], v[10:13]
	s_setprio 0
	s_barrier
	s_add_i32 s50, s50, 2
	s_add_u32 s12, s12, 0x8000
	s_addc_u32 s13, s13, 0
	s_add_u32 s44, s44, 0x8000
	s_addc_u32 s45, s45, 0
	s_cmp_gt_u32 s50, 13
	s_cbranch_scc0 .LBB0_981
	s_lshl_b32 s4, s4, 8
	s_add_i32 s4, s4, s58
	v_or_b32_e32 v138, s4, v1
	v_ashrrev_i32_e32 v139, 31, v138
	v_lshl_add_u64 v[140:141], v[138:139], 2, s[30:31]
	v_lshrrev_b32_e32 v218, 4, v142
	v_and_b32_e32 v219, 1, v218
	v_lshrrev_b32_e32 v218, 1, v218
	v_lshlrev_b32_e32 v222, 7, v219
	v_lshl_add_u32 v222, v218, 9, v222
	v_mov_b32_e32 v223, 0
	v_lshl_add_u64 v[220:221], v[140:141], 0, v[222:223]
	global_load_dword v224, v[220:221], off sc1
	global_load_dword v225, v[220:221], off offset:64 sc1
	s_and_b64 vcc, exec, s[28:29]
	s_cbranch_vccz .LBB0_984
	s_barrier
.LBB0_984:
	s_lshl_b32 s5, s5, 7
	s_or_b32 s5, s5, s59
	s_ashr_i32 s4, s4, 7
	s_ashr_i32 s37, s5, 6
	s_mul_i32 s4, s4, 44
	s_add_i32 s4, s4, s37
	s_ashr_i32 s5, s4, 31
	s_lshl_b64 s[12:13], s[4:5], 14
	v_mov_b32_e32 v150, v126
	v_mov_b32_e32 v151, v118
	v_mov_b32_e32 v118, v127
	v_mov_b32_e32 v126, v128
	v_mov_b32_e32 v127, v120
	v_mov_b32_e32 v120, v129
	v_mov_b32_e32 v129, v114
	v_mov_b32_e32 v114, v123
	v_mov_b32_e32 v153, v116
	v_mov_b32_e32 v116, v125
	v_mov_b32_e32 v128, v122
	v_mov_b32_e32 v152, v124
	v_lshlrev_b32_e32 v122, 6, v138
	v_lshlrev_b32_e32 v123, 2, v138
	v_or_b32_e32 v124, 16, v138
	v_and_or_b32 v122, v122, s60, v142
	v_and_b32_e32 v123, 32, v123
	s_add_u32 s12, s34, s12
	v_ashrrev_i32_e32 v125, 31, v124
	v_bitop3_b32 v149, v122, s62, v123 bitop3:0xde
	s_addc_u32 s13, s35, s13
	s_waitcnt vmcnt(0)
; __device__ __forceinline__ unsigned cvt_pk_bf16(float lo, float hi) { unsigned r; asm volatile("v_cvt_pk_bf16_f32 %0, %1, %2" : "=v"(r) : "v"(lo), "v"(hi)); return r; }
; __device__ __forceinline__ float silu_f(float x) { return x * fast_rcp(1.0f + fast_exp2(-1.4426950408889634f * x)); }
;     __device__ __forceinline__ void operator()(const f32x4 (&acc)[2][2][4][2], const Unit& u, int wr, int wc, int fr, int fq) const {
;     ...
;             for (int m = 0; m < 4; ++m) { const int row = row0 + ai * HALF + m * 16;
;                 const float r = 1.0f / sqrtf(__hip_atomic_load(ss + row, __ATOMIC_RELAXED, __HIP_MEMORY_SCOPE_AGENT) * (1.0f / 1024.0f) + 1e-6f);
;                 float a[8];
; #pragma unroll
;                 for (int n = 0; n < 2; ++n)
; #pragma unroll
;                     for (int j = 0; j < 4; ++j) a[4 * n + j] = silu_f(acc[ai][0][m][n][j] * r) * (acc[ai][1][m][n][j] * r);
;                 u32x4 w; w.x = cvt_pk_bf16(a[0], a[1]); w.y = cvt_pk_bf16(a[2], a[3]); w.z = cvt_pk_bf16(a[4], a[5]); w.w = cvt_pk_bf16(a[6], a[7]);
	v_fmamk_f32 v224, v224, 0x3a800000, v147
	v_mul_f32_e32 v226, 0x4f800000, v224
	v_cmp_gt_f32_e32 vcc, s66, v224
	s_nop 1
	v_cndmask_b32_e32 v224, v224, v226, vcc
	v_sqrt_f32_e32 v226, v224
	s_nop 0
	v_add_u32_e32 v227, -1, v226
	v_add_u32_e32 v228, 1, v226
	v_fma_f32 v229, -v227, v226, v224
	v_fma_f32 v230, -v228, v226, v224
	v_cmp_ge_f32_e64 s[4:5], 0, v229
	s_nop 1
	v_cndmask_b32_e64 v226, v226, v227, s[4:5]
	v_cmp_lt_f32_e64 s[4:5], 0, v230
	s_nop 1
	v_cndmask_b32_e64 v226, v226, v228, s[4:5]
	v_mul_f32_e32 v227, 0x37800000, v226
	v_cndmask_b32_e32 v226, v226, v227, vcc
	v_cmp_class_f32_e32 vcc, v224, v148
	s_nop 1
	v_cndmask_b32_e32 v224, v226, v224, vcc
	v_div_scale_f32 v226, s[4:5], v224, v224, 1.0
	v_rcp_f32_e32 v227, v226
	v_div_scale_f32 v228, vcc, 1.0, v224, 1.0
	v_fma_f32 v229, -v226, v227, 1.0
	v_fmac_f32_e32 v227, v229, v227
	v_mul_f32_e32 v229, v228, v227
	v_fma_f32 v230, -v226, v229, v228
	v_fmac_f32_e32 v229, v230, v227
	v_fma_f32 v226, -v226, v229, v228
	v_div_fmas_f32 v226, v226, v227, v229
	v_div_fixup_f32 v224, v226, v224, 1.0
	v_fmamk_f32 v225, v225, 0x3a800000, v147
	v_mul_f32_e32 v226, 0x4f800000, v225
	v_cmp_gt_f32_e32 vcc, s66, v225
	s_nop 1
	v_cndmask_b32_e32 v225, v225, v226, vcc
	v_sqrt_f32_e32 v226, v225
	s_nop 0
	v_add_u32_e32 v227, -1, v226
	v_add_u32_e32 v228, 1, v226
	v_fma_f32 v229, -v227, v226, v225
	v_fma_f32 v230, -v228, v226, v225
	v_cmp_ge_f32_e64 s[4:5], 0, v229
	s_nop 1
	v_cndmask_b32_e64 v226, v226, v227, s[4:5]
	v_cmp_lt_f32_e64 s[4:5], 0, v230
	s_nop 1
	v_cndmask_b32_e64 v226, v226, v228, s[4:5]
	v_mul_f32_e32 v227, 0x37800000, v226
	v_cndmask_b32_e32 v226, v226, v227, vcc
	v_cmp_class_f32_e32 vcc, v225, v148
	s_nop 1
	v_cndmask_b32_e32 v225, v226, v225, vcc
	v_div_scale_f32 v226, s[4:5], v225, v225, 1.0
	v_rcp_f32_e32 v227, v226
	v_div_scale_f32 v228, vcc, 1.0, v225, 1.0
	v_fma_f32 v229, -v226, v227, 1.0
	v_fmac_f32_e32 v227, v229, v227
	v_mul_f32_e32 v229, v228, v227
	v_fma_f32 v230, -v226, v229, v228
	v_fmac_f32_e32 v229, v230, v227
	v_fma_f32 v226, -v226, v229, v228
	v_div_fmas_f32 v226, v226, v227, v229
	v_div_fixup_f32 v225, v226, v225, 1.0
	s_lshl_b32 s98, s58, 7
	s_lshl_b32 s99, s59, 6
	s_add_i32 s98, s98, s99
	s_add_i32 s98, s98, 0x24000
	v_lshlrev_b32_e32 v226, 5, v1
	v_add_u32_e32 v226, s98, v226
	v_lshrrev_b32_e32 v227, 1, v142
	v_add_u32_e32 v227, v226, v227
	ds_write_b64 v227, v[224:225]
	ds_read_b128 v[232:235], v226
	ds_read_b128 v[236:239], v226 offset:16
	s_waitcnt lgkmcnt(0)
	s_nop 1
	s_nop 0
	s_nop 1
	s_nop 1
	s_nop 1
	v_mov_b32_e32 v132, v232
	v_pk_mul_f32 v[150:151], v[150:151], v[132:133] op_sel_hi:[1,0]
	v_pk_mul_f32 v[118:119], v[118:119], v[132:133] op_sel_hi:[1,0]
	v_pk_mul_f32 v[126:127], v[126:127], v[132:133] op_sel_hi:[1,0]
	v_pk_mul_f32 v[120:121], v[120:121], v[132:133] op_sel_hi:[1,0]
	v_pk_mul_f32 v[114:115], v[114:115], v[132:133] op_sel_hi:[1,0]
	v_pk_mul_f32 v[116:117], v[116:117], v[132:133] op_sel_hi:[1,0]
	v_pk_mul_f32 v[128:129], v[128:129], v[132:133] op_sel_hi:[1,0]
	v_pk_mul_f32 v[152:153], v[152:153], v[132:133] op_sel_hi:[1,0]
	v_mul_f32_e32 v132, 0xbfb8aa3b, v151
	v_mul_f32_e32 v139, 0xbfb8aa3b, v119
	v_mul_f32_e32 v154, 0xbfb8aa3b, v127
	v_mul_f32_e32 v155, 0xbfb8aa3b, v121
	v_mul_f32_e32 v157, 0xbfb8aa3b, v115
	v_mul_f32_e32 v159, 0xbfb8aa3b, v117
	v_mul_f32_e32 v156, 0xbfb8aa3b, v129
	v_mul_f32_e32 v158, 0xbfb8aa3b, v153
	v_exp_f32_e32 v132, v132
	v_exp_f32_e32 v139, v139
	v_exp_f32_e32 v154, v154
	v_exp_f32_e32 v155, v155
	v_exp_f32_e32 v157, v157
	v_exp_f32_e32 v159, v159
	v_exp_f32_e32 v156, v156
	v_exp_f32_e32 v158, v158
	v_add_f32_e32 v132, 1.0, v132
	v_add_f32_e32 v139, 1.0, v139
	v_add_f32_e32 v154, 1.0, v154
	v_add_f32_e32 v155, 1.0, v155
	v_add_f32_e32 v157, 1.0, v157
	v_add_f32_e32 v159, 1.0, v159
	v_add_f32_e32 v156, 1.0, v156
	v_add_f32_e32 v158, 1.0, v158
	v_rcp_f32_e32 v132, v132
	v_rcp_f32_e32 v139, v139
	v_rcp_f32_e32 v154, v154
	v_rcp_f32_e32 v155, v155
	v_rcp_f32_e32 v157, v157
	v_rcp_f32_e32 v159, v159
	v_rcp_f32_e32 v156, v156
	v_rcp_f32_e32 v158, v158
	v_mul_f32_e32 v132, v151, v132
	v_mul_f32_e32 v119, v119, v139
	v_mul_f32_e32 v127, v127, v154
	v_mul_f32_e32 v121, v121, v155
	v_mul_f32_e32 v115, v115, v157
	v_mul_f32_e32 v117, v117, v159
	v_mul_f32_e32 v129, v129, v156
	v_mul_f32_e32 v139, v153, v158
	v_mul_f32_e32 v132, v150, v132
	v_mul_f32_e32 v118, v118, v119
	v_mul_f32_e32 v119, v126, v127
	v_mul_f32_e32 v120, v120, v121
	v_mul_f32_e32 v126, v114, v115
	v_mul_f32_e32 v117, v116, v117
	v_cvt_pk_bf16_f32 v114, v132, v118
	v_cvt_pk_bf16_f32 v115, v119, v120
	v_mul_f32_e32 v121, v128, v129
	v_mul_f32_e32 v127, v152, v139
	v_cvt_pk_bf16_f32 v116, v121, v126
	v_cvt_pk_bf16_f32 v117, v127, v117
	global_store_dwordx4 v149, v[114:117], s[12:13]
	s_nop 1
	v_lshl_add_u64 v[114:115], v[124:125], 2, s[30:31]
	s_nop 0
	v_mov_b32_e32 v114, v110
	v_mov_b32_e32 v110, v112
	v_mov_b32_e32 v112, v106
	v_mov_b32_e32 v106, v108
	v_or_b32_e32 v108, 32, v138
	v_lshrrev_b32_e32 v117, 3, v124
	v_mov_b32_e32 v115, v102
	v_mov_b32_e32 v102, v111
	v_mov_b32_e32 v111, v104
	v_mov_b32_e32 v104, v113
	v_mov_b32_e32 v113, v98
	v_mov_b32_e32 v98, v107
	v_mov_b32_e32 v107, v100
	v_mov_b32_e32 v100, v109
	v_ashrrev_i32_e32 v109, 31, v108
	v_and_or_b32 v120, v117, 10, s61
	s_nop 0
	s_nop 1
	v_lshl_add_u64 v[116:117], v[108:109], 2, s[30:31]
	v_lshlrev_b32_e32 v109, 10, v120
	v_bitop3_b32 v109, v122, v109, v123 bitop3:0xde
	s_nop 1
	s_nop 1
	s_nop 1
	v_mov_b32_e32 v118, v233
	v_pk_mul_f32 v[100:101], v[100:101], v[118:119] op_sel_hi:[1,0]
	v_pk_mul_f32 v[114:115], v[114:115], v[118:119] op_sel_hi:[1,0]
	v_pk_mul_f32 v[102:103], v[102:103], v[118:119] op_sel_hi:[1,0]
; __host__ __device__ __forceinline__ size_t img_off(int row, int col, int nkt) { return ((size_t)((row >> 7) * nkt + (col >> 6)) << 14) + (size_t)lds_byte(row & 127, col & 63); }
; __device__ __forceinline__ unsigned cvt_pk_bf16(float lo, float hi) { unsigned r; asm volatile("v_cvt_pk_bf16_f32 %0, %1, %2" : "=v"(r) : "v"(lo), "v"(hi)); return r; }
; __device__ __forceinline__ float silu_f(float x) { return x * fast_rcp(1.0f + fast_exp2(-1.4426950408889634f * x)); }
;     __device__ __forceinline__ void operator()(const f32x4 (&acc)[2][2][4][2], const Unit& u, int wr, int wc, int fr, int fq) const {
;     ...
;             for (int m = 0; m < 4; ++m) { const int row = row0 + ai * HALF + m * 16;
;                 const float r = 1.0f / sqrtf(__hip_atomic_load(ss + row, __ATOMIC_RELAXED, __HIP_MEMORY_SCOPE_AGENT) * (1.0f / 1024.0f) + 1e-6f);
;                 float a[8];
; #pragma unroll
;                 for (int n = 0; n < 2; ++n)
; #pragma unroll
;                     for (int j = 0; j < 4; ++j) a[4 * n + j] = silu_f(acc[ai][0][m][n][j] * r) * (acc[ai][1][m][n][j] * r);
;                 u32x4 w; w.x = cvt_pk_bf16(a[0], a[1]); w.y = cvt_pk_bf16(a[2], a[3]); w.z = cvt_pk_bf16(a[4], a[5]); w.w = cvt_pk_bf16(a[6], a[7]);
;                 *(u32x4*)((char*)H + img_off(row, col0, 44)) = w; }
	v_pk_mul_f32 v[110:111], v[110:111], v[118:119] op_sel_hi:[1,0]
	v_pk_mul_f32 v[104:105], v[104:105], v[118:119] op_sel_hi:[1,0]
	v_pk_mul_f32 v[112:113], v[112:113], v[118:119] op_sel_hi:[1,0]
	v_pk_mul_f32 v[98:99], v[98:99], v[118:119] op_sel_hi:[1,0]
	v_pk_mul_f32 v[106:107], v[106:107], v[118:119] op_sel_hi:[1,0]
	v_mul_f32_e32 v127, 0xbfb8aa3b, v101
	v_mul_f32_e32 v118, 0xbfb8aa3b, v115
	v_mul_f32_e32 v119, 0xbfb8aa3b, v103
	v_mul_f32_e32 v120, 0xbfb8aa3b, v111
	v_mul_f32_e32 v121, 0xbfb8aa3b, v105
	v_mul_f32_e32 v124, 0xbfb8aa3b, v113
	v_mul_f32_e32 v125, 0xbfb8aa3b, v99
	v_mul_f32_e32 v126, 0xbfb8aa3b, v107
	v_exp_f32_e32 v127, v127
	v_exp_f32_e32 v118, v118
	v_exp_f32_e32 v119, v119
	v_exp_f32_e32 v120, v120
	v_exp_f32_e32 v121, v121
	v_exp_f32_e32 v124, v124
	v_exp_f32_e32 v125, v125
	v_exp_f32_e32 v126, v126
	v_add_f32_e32 v127, 1.0, v127
	v_add_f32_e32 v118, 1.0, v118
	v_add_f32_e32 v119, 1.0, v119
	v_add_f32_e32 v120, 1.0, v120
	v_add_f32_e32 v121, 1.0, v121
	v_add_f32_e32 v124, 1.0, v124
	v_add_f32_e32 v125, 1.0, v125
	v_add_f32_e32 v126, 1.0, v126
	v_rcp_f32_e32 v127, v127
	v_rcp_f32_e32 v118, v118
	v_rcp_f32_e32 v119, v119
	v_rcp_f32_e32 v120, v120
	v_rcp_f32_e32 v121, v121
	v_rcp_f32_e32 v124, v124
	v_rcp_f32_e32 v125, v125
	v_rcp_f32_e32 v126, v126
	v_mul_f32_e32 v101, v101, v127
	v_mul_f32_e32 v115, v115, v118
	v_mul_f32_e32 v103, v103, v119
	v_mul_f32_e32 v111, v111, v120
	v_mul_f32_e32 v105, v105, v121
	v_mul_f32_e32 v113, v113, v124
	v_mul_f32_e32 v99, v99, v125
	v_mul_f32_e32 v107, v107, v126
	v_mul_f32_e32 v101, v100, v101
	v_mul_f32_e32 v114, v114, v115
	v_mul_f32_e32 v102, v102, v103
	v_mul_f32_e32 v103, v110, v111
	v_mul_f32_e32 v104, v104, v105
	v_mul_f32_e32 v105, v112, v113
	v_mul_f32_e32 v110, v98, v99
	v_mul_f32_e32 v106, v106, v107
	v_cvt_pk_bf16_f32 v98, v114, v102
	v_cvt_pk_bf16_f32 v99, v103, v104
	v_cvt_pk_bf16_f32 v100, v105, v110
	v_cvt_pk_bf16_f32 v101, v106, v101
	global_store_dwordx4 v109, v[98:101], s[12:13]
	s_nop 0
	s_nop 0
	v_mov_b32_e32 v98, v94
	v_mov_b32_e32 v94, v96
	v_mov_b32_e32 v96, v90
	v_mov_b32_e32 v90, v92
	v_or_b32_e32 v92, 48, v138
	v_lshrrev_b32_e32 v101, 3, v108
	v_mov_b32_e32 v99, v86
	v_mov_b32_e32 v86, v95
	v_mov_b32_e32 v95, v88
	v_mov_b32_e32 v88, v97
	v_mov_b32_e32 v97, v82
	v_mov_b32_e32 v82, v91
	v_mov_b32_e32 v91, v84
	v_mov_b32_e32 v84, v93
	v_ashrrev_i32_e32 v93, 31, v92
	v_and_or_b32 v104, v101, 12, s61
	s_nop 0
	s_nop 1
	v_lshl_add_u64 v[100:101], v[92:93], 2, s[30:31]
	v_lshlrev_b32_e32 v93, 10, v104
	v_bitop3_b32 v93, v122, v93, v123 bitop3:0xde
	s_nop 1
	s_nop 1
	s_nop 1
	v_mov_b32_e32 v102, v234
	v_pk_mul_f32 v[84:85], v[84:85], v[102:103] op_sel_hi:[1,0]
	v_pk_mul_f32 v[98:99], v[98:99], v[102:103] op_sel_hi:[1,0]
	v_pk_mul_f32 v[86:87], v[86:87], v[102:103] op_sel_hi:[1,0]
	v_pk_mul_f32 v[94:95], v[94:95], v[102:103] op_sel_hi:[1,0]
	v_pk_mul_f32 v[88:89], v[88:89], v[102:103] op_sel_hi:[1,0]
	v_pk_mul_f32 v[96:97], v[96:97], v[102:103] op_sel_hi:[1,0]
	v_pk_mul_f32 v[82:83], v[82:83], v[102:103] op_sel_hi:[1,0]
	v_pk_mul_f32 v[90:91], v[90:91], v[102:103] op_sel_hi:[1,0]
	v_mul_f32_e32 v109, 0xbfb8aa3b, v85
	v_mul_f32_e32 v102, 0xbfb8aa3b, v99
	v_mul_f32_e32 v103, 0xbfb8aa3b, v87
	v_mul_f32_e32 v104, 0xbfb8aa3b, v95
	v_mul_f32_e32 v105, 0xbfb8aa3b, v89
	v_mul_f32_e32 v106, 0xbfb8aa3b, v97
	v_mul_f32_e32 v107, 0xbfb8aa3b, v83
	v_mul_f32_e32 v108, 0xbfb8aa3b, v91
	v_exp_f32_e32 v109, v109
	v_exp_f32_e32 v102, v102
	v_exp_f32_e32 v103, v103
	v_exp_f32_e32 v104, v104
	v_exp_f32_e32 v105, v105
	v_exp_f32_e32 v106, v106
	v_exp_f32_e32 v107, v107
	v_exp_f32_e32 v108, v108
	v_add_f32_e32 v109, 1.0, v109
	v_add_f32_e32 v102, 1.0, v102
	v_add_f32_e32 v103, 1.0, v103
	v_add_f32_e32 v104, 1.0, v104
	v_add_f32_e32 v105, 1.0, v105
	v_add_f32_e32 v106, 1.0, v106
	v_add_f32_e32 v107, 1.0, v107
	v_add_f32_e32 v108, 1.0, v108
	v_rcp_f32_e32 v109, v109
	v_rcp_f32_e32 v102, v102
	v_rcp_f32_e32 v103, v103
	v_rcp_f32_e32 v104, v104
	v_rcp_f32_e32 v105, v105
	v_rcp_f32_e32 v106, v106
	v_rcp_f32_e32 v107, v107
	v_rcp_f32_e32 v108, v108
	v_mul_f32_e32 v85, v85, v109
	v_mul_f32_e32 v99, v99, v102
	v_mul_f32_e32 v87, v87, v103
	v_mul_f32_e32 v95, v95, v104
	v_mul_f32_e32 v89, v89, v105
	v_mul_f32_e32 v97, v97, v106
	v_mul_f32_e32 v83, v83, v107
	v_mul_f32_e32 v91, v91, v108
	v_mul_f32_e32 v85, v84, v85
	v_mul_f32_e32 v98, v98, v99
	v_mul_f32_e32 v86, v86, v87
	v_mul_f32_e32 v87, v94, v95
	v_mul_f32_e32 v88, v88, v89
	v_mul_f32_e32 v89, v96, v97
	v_mul_f32_e32 v94, v82, v83
	v_mul_f32_e32 v90, v90, v91
	v_cvt_pk_bf16_f32 v82, v98, v86
	v_cvt_pk_bf16_f32 v83, v87, v88
	v_cvt_pk_bf16_f32 v84, v89, v94
	v_cvt_pk_bf16_f32 v85, v90, v85
	global_store_dwordx4 v93, v[82:85], s[12:13]
	s_nop 0
	s_nop 0
	v_mov_b32_e32 v82, v78
	v_mov_b32_e32 v78, v80
	v_mov_b32_e32 v80, v74
	v_mov_b32_e32 v74, v76
	v_mov_b32_e32 v83, v70
	v_mov_b32_e32 v70, v79
	v_mov_b32_e32 v79, v72
	v_mov_b32_e32 v72, v81
	v_mov_b32_e32 v81, v66
	v_mov_b32_e32 v66, v75
	v_mov_b32_e32 v75, v68
	v_mov_b32_e32 v68, v77
	s_nop 0
	v_lshrrev_b32_e32 v84, 3, v92
	v_and_or_b32 v84, v84, 14, s61
	v_lshlrev_b32_e32 v84, 10, v84
	v_bitop3_b32 v84, v122, v84, v123 bitop3:0xde
	s_nop 1
	s_nop 1
	s_nop 1
	v_mov_b32_e32 v76, v235
	v_pk_mul_f32 v[68:69], v[68:69], v[76:77] op_sel_hi:[1,0]
	v_pk_mul_f32 v[82:83], v[82:83], v[76:77] op_sel_hi:[1,0]
	v_pk_mul_f32 v[70:71], v[70:71], v[76:77] op_sel_hi:[1,0]
	v_pk_mul_f32 v[78:79], v[78:79], v[76:77] op_sel_hi:[1,0]
	v_pk_mul_f32 v[72:73], v[72:73], v[76:77] op_sel_hi:[1,0]
	v_pk_mul_f32 v[80:81], v[80:81], v[76:77] op_sel_hi:[1,0]
	v_pk_mul_f32 v[66:67], v[66:67], v[76:77] op_sel_hi:[1,0]
; __host__ __device__ __forceinline__ size_t img_off(int row, int col, int nkt) { return ((size_t)((row >> 7) * nkt + (col >> 6)) << 14) + (size_t)lds_byte(row & 127, col & 63); }
; __device__ __forceinline__ unsigned cvt_pk_bf16(float lo, float hi) { unsigned r; asm volatile("v_cvt_pk_bf16_f32 %0, %1, %2" : "=v"(r) : "v"(lo), "v"(hi)); return r; }
; __device__ __forceinline__ float silu_f(float x) { return x * fast_rcp(1.0f + fast_exp2(-1.4426950408889634f * x)); }
;     __device__ __forceinline__ void operator()(const f32x4 (&acc)[2][2][4][2], const Unit& u, int wr, int wc, int fr, int fq) const {
;     ...
;             for (int m = 0; m < 4; ++m) { const int row = row0 + ai * HALF + m * 16;
;                 const float r = 1.0f / sqrtf(__hip_atomic_load(ss + row, __ATOMIC_RELAXED, __HIP_MEMORY_SCOPE_AGENT) * (1.0f / 1024.0f) + 1e-6f);
;                 float a[8];
; #pragma unroll
;                 for (int n = 0; n < 2; ++n)
; #pragma unroll
;                     for (int j = 0; j < 4; ++j) a[4 * n + j] = silu_f(acc[ai][0][m][n][j] * r) * (acc[ai][1][m][n][j] * r);
;                 u32x4 w; w.x = cvt_pk_bf16(a[0], a[1]); w.y = cvt_pk_bf16(a[2], a[3]); w.z = cvt_pk_bf16(a[4], a[5]); w.w = cvt_pk_bf16(a[6], a[7]);
;                 *(u32x4*)((char*)H + img_off(row, col0, 44)) = w; }
	v_pk_mul_f32 v[74:75], v[74:75], v[76:77] op_sel_hi:[1,0]
	v_mul_f32_e32 v90, 0xbfb8aa3b, v69
	v_mul_f32_e32 v76, 0xbfb8aa3b, v83
	v_mul_f32_e32 v77, 0xbfb8aa3b, v71
	v_mul_f32_e32 v85, 0xbfb8aa3b, v79
	v_mul_f32_e32 v86, 0xbfb8aa3b, v73
	v_mul_f32_e32 v87, 0xbfb8aa3b, v81
	v_mul_f32_e32 v88, 0xbfb8aa3b, v67
	v_mul_f32_e32 v89, 0xbfb8aa3b, v75
	v_exp_f32_e32 v90, v90
	v_exp_f32_e32 v76, v76
	v_exp_f32_e32 v77, v77
	v_exp_f32_e32 v85, v85
	v_exp_f32_e32 v86, v86
	v_exp_f32_e32 v87, v87
	v_exp_f32_e32 v88, v88
	v_exp_f32_e32 v89, v89
	v_add_f32_e32 v90, 1.0, v90
	v_add_f32_e32 v76, 1.0, v76
	v_add_f32_e32 v77, 1.0, v77
	v_add_f32_e32 v85, 1.0, v85
	v_add_f32_e32 v86, 1.0, v86
	v_add_f32_e32 v87, 1.0, v87
	v_add_f32_e32 v88, 1.0, v88
	v_add_f32_e32 v89, 1.0, v89
	v_rcp_f32_e32 v90, v90
	v_rcp_f32_e32 v76, v76
	v_rcp_f32_e32 v77, v77
	v_rcp_f32_e32 v85, v85
	v_rcp_f32_e32 v86, v86
	v_rcp_f32_e32 v87, v87
	v_rcp_f32_e32 v88, v88
	v_rcp_f32_e32 v89, v89
	v_mul_f32_e32 v69, v69, v90
	v_mul_f32_e32 v76, v83, v76
	v_mul_f32_e32 v71, v71, v77
	v_mul_f32_e32 v77, v79, v85
	v_mul_f32_e32 v73, v73, v86
	v_mul_f32_e32 v79, v81, v87
	v_mul_f32_e32 v67, v67, v88
	v_mul_f32_e32 v75, v75, v89
	v_mul_f32_e32 v69, v68, v69
	v_mul_f32_e32 v76, v82, v76
	v_mul_f32_e32 v70, v70, v71
	v_mul_f32_e32 v71, v78, v77
	v_mul_f32_e32 v72, v72, v73
	v_mul_f32_e32 v73, v80, v79
	v_mul_f32_e32 v77, v66, v67
	v_mul_f32_e32 v74, v74, v75
	v_cvt_pk_bf16_f32 v66, v76, v70
	v_cvt_pk_bf16_f32 v67, v71, v72
	v_cvt_pk_bf16_f32 v68, v73, v77
	v_cvt_pk_bf16_f32 v69, v74, v69
	global_store_dwordx4 v84, v[66:69], s[12:13]
	s_nop 0
	s_nop 0
	v_mov_b32_e32 v67, v54
	v_mov_b32_e32 v54, v63
	v_mov_b32_e32 v63, v56
	v_mov_b32_e32 v56, v65
	v_mov_b32_e32 v65, v50
	v_mov_b32_e32 v50, v59
	v_add_u32_e32 v59, 0x80, v138
	v_mov_b32_e32 v66, v62
	v_mov_b32_e32 v62, v64
	v_mov_b32_e32 v64, v58
	v_mov_b32_e32 v68, v60
	v_mov_b32_e32 v69, v52
	v_mov_b32_e32 v52, v61
	v_mov_b32_e32 v58, s37
	v_ashrrev_i32_e32 v60, 7, v59
	v_lshlrev_b32_e32 v61, 6, v59
	v_lshlrev_b32_e32 v71, 2, v59
	v_mad_u64_u32 v[58:59], s[4:5], v60, 44, v[58:59]
	v_and_or_b32 v60, v61, s60, v142
	v_and_b32_e32 v61, 32, v71
	v_bitop3_b32 v132, v60, s62, v61 bitop3:0xde
	v_ashrrev_i32_e32 v59, 31, v58
	v_lshlrev_b64 v[58:59], 14, v[58:59]
	v_lshl_add_u64 v[58:59], s[34:35], 0, v[58:59]
	s_nop 1
	s_nop 1
	s_nop 1
	v_lshl_add_u64 v[60:61], v[58:59], 0, v[132:133]
	v_mov_b32_e32 v70, v236
	v_pk_mul_f32 v[52:53], v[52:53], v[70:71] op_sel_hi:[1,0]
	v_pk_mul_f32 v[66:67], v[66:67], v[70:71] op_sel_hi:[1,0]
	v_pk_mul_f32 v[54:55], v[54:55], v[70:71] op_sel_hi:[1,0]
	v_pk_mul_f32 v[62:63], v[62:63], v[70:71] op_sel_hi:[1,0]
	v_pk_mul_f32 v[56:57], v[56:57], v[70:71] op_sel_hi:[1,0]
	v_pk_mul_f32 v[64:65], v[64:65], v[70:71] op_sel_hi:[1,0]
	v_pk_mul_f32 v[50:51], v[50:51], v[70:71] op_sel_hi:[1,0]
	v_pk_mul_f32 v[68:69], v[68:69], v[70:71] op_sel_hi:[1,0]
	v_mul_f32_e32 v77, 0xbfb8aa3b, v53
	v_mul_f32_e32 v70, 0xbfb8aa3b, v67
	v_mul_f32_e32 v71, 0xbfb8aa3b, v55
	v_mul_f32_e32 v72, 0xbfb8aa3b, v63
	v_mul_f32_e32 v73, 0xbfb8aa3b, v57
	v_mul_f32_e32 v74, 0xbfb8aa3b, v65
	v_mul_f32_e32 v75, 0xbfb8aa3b, v51
	v_mul_f32_e32 v76, 0xbfb8aa3b, v69
	v_exp_f32_e32 v77, v77
	v_exp_f32_e32 v70, v70
	v_exp_f32_e32 v71, v71
	v_exp_f32_e32 v72, v72
	v_exp_f32_e32 v73, v73
	v_exp_f32_e32 v74, v74
	v_exp_f32_e32 v75, v75
	v_exp_f32_e32 v76, v76
	v_add_f32_e32 v77, 1.0, v77
	v_add_f32_e32 v70, 1.0, v70
	v_add_f32_e32 v71, 1.0, v71
	v_add_f32_e32 v72, 1.0, v72
	v_add_f32_e32 v73, 1.0, v73
	v_add_f32_e32 v74, 1.0, v74
	v_add_f32_e32 v75, 1.0, v75
	v_add_f32_e32 v76, 1.0, v76
	v_rcp_f32_e32 v77, v77
	v_rcp_f32_e32 v70, v70
	v_rcp_f32_e32 v71, v71
	v_rcp_f32_e32 v72, v72
	v_rcp_f32_e32 v73, v73
	v_rcp_f32_e32 v74, v74
	v_rcp_f32_e32 v75, v75
	v_rcp_f32_e32 v76, v76
	v_mul_f32_e32 v53, v53, v77
	v_mul_f32_e32 v67, v67, v70
	v_mul_f32_e32 v55, v55, v71
	v_mul_f32_e32 v63, v63, v72
	v_mul_f32_e32 v57, v57, v73
	v_mul_f32_e32 v65, v65, v74
	v_mul_f32_e32 v51, v51, v75
	v_mul_f32_e32 v69, v69, v76
	v_mul_f32_e32 v53, v52, v53
	v_mul_f32_e32 v66, v66, v67
	v_mul_f32_e32 v54, v54, v55
	v_mul_f32_e32 v55, v62, v63
	v_mul_f32_e32 v56, v56, v57
	v_mul_f32_e32 v57, v64, v65
	v_mul_f32_e32 v62, v50, v51
	v_mul_f32_e32 v63, v68, v69
	v_cvt_pk_bf16_f32 v50, v66, v54
	v_cvt_pk_bf16_f32 v51, v55, v56
	v_cvt_pk_bf16_f32 v52, v57, v62
	v_cvt_pk_bf16_f32 v53, v63, v53
	global_store_dwordx4 v[60:61], v[50:53], off
	s_nop 0
	s_nop 0
	v_mov_b32_e32 v50, v46
	v_mov_b32_e32 v46, v48
	v_mov_b32_e32 v48, v42
	v_mov_b32_e32 v42, v44
	v_add_u32_e32 v44, 0x90, v138
	v_mov_b32_e32 v51, v38
	v_mov_b32_e32 v38, v47
	v_mov_b32_e32 v47, v40
	v_mov_b32_e32 v40, v49
	v_mov_b32_e32 v49, v34
	v_mov_b32_e32 v34, v43
	v_mov_b32_e32 v43, v36
	v_mov_b32_e32 v36, v45
	v_lshrrev_b32_e32 v45, 3, v44
	v_lshlrev_b32_e32 v53, 6, v44
	v_lshlrev_b32_e32 v44, 2, v44
	v_and_or_b32 v45, v45, 10, s61
	v_and_or_b32 v53, v53, s60, v142
	v_and_b32_e32 v44, 32, v44
	v_lshlrev_b32_e32 v45, 10, v45
	v_bitop3_b32 v132, v53, v45, v44 bitop3:0xde
	s_nop 0
	s_nop 1
	s_nop 0
	s_nop 1
	s_nop 1
	s_nop 1
	v_lshl_add_u64 v[44:45], v[58:59], 0, v[132:133]
	v_mov_b32_e32 v52, v237
	v_pk_mul_f32 v[36:37], v[36:37], v[52:53] op_sel_hi:[1,0]
	v_pk_mul_f32 v[50:51], v[50:51], v[52:53] op_sel_hi:[1,0]
	v_pk_mul_f32 v[38:39], v[38:39], v[52:53] op_sel_hi:[1,0]
	v_pk_mul_f32 v[46:47], v[46:47], v[52:53] op_sel_hi:[1,0]
	v_pk_mul_f32 v[40:41], v[40:41], v[52:53] op_sel_hi:[1,0]
	v_pk_mul_f32 v[48:49], v[48:49], v[52:53] op_sel_hi:[1,0]
	v_pk_mul_f32 v[34:35], v[34:35], v[52:53] op_sel_hi:[1,0]
	v_pk_mul_f32 v[42:43], v[42:43], v[52:53] op_sel_hi:[1,0]
; __host__ __device__ __forceinline__ size_t img_off(int row, int col, int nkt) { return ((size_t)((row >> 7) * nkt + (col >> 6)) << 14) + (size_t)lds_byte(row & 127, col & 63); }
; __device__ __forceinline__ unsigned cvt_pk_bf16(float lo, float hi) { unsigned r; asm volatile("v_cvt_pk_bf16_f32 %0, %1, %2" : "=v"(r) : "v"(lo), "v"(hi)); return r; }
; __device__ __forceinline__ float silu_f(float x) { return x * fast_rcp(1.0f + fast_exp2(-1.4426950408889634f * x)); }
;     __device__ __forceinline__ void operator()(const f32x4 (&acc)[2][2][4][2], const Unit& u, int wr, int wc, int fr, int fq) const {
;     ...
;             for (int m = 0; m < 4; ++m) { const int row = row0 + ai * HALF + m * 16;
;                 const float r = 1.0f / sqrtf(__hip_atomic_load(ss + row, __ATOMIC_RELAXED, __HIP_MEMORY_SCOPE_AGENT) * (1.0f / 1024.0f) + 1e-6f);
;                 float a[8];
; #pragma unroll
;                 for (int n = 0; n < 2; ++n)
; #pragma unroll
;                     for (int j = 0; j < 4; ++j) a[4 * n + j] = silu_f(acc[ai][0][m][n][j] * r) * (acc[ai][1][m][n][j] * r);
;                 u32x4 w; w.x = cvt_pk_bf16(a[0], a[1]); w.y = cvt_pk_bf16(a[2], a[3]); w.z = cvt_pk_bf16(a[4], a[5]); w.w = cvt_pk_bf16(a[6], a[7]);
;                 *(u32x4*)((char*)H + img_off(row, col0, 44)) = w; }
	v_mul_f32_e32 v61, 0xbfb8aa3b, v37
	v_mul_f32_e32 v52, 0xbfb8aa3b, v51
	v_mul_f32_e32 v53, 0xbfb8aa3b, v39
	v_mul_f32_e32 v54, 0xbfb8aa3b, v47
	v_mul_f32_e32 v55, 0xbfb8aa3b, v41
	v_mul_f32_e32 v56, 0xbfb8aa3b, v49
	v_mul_f32_e32 v57, 0xbfb8aa3b, v35
	v_mul_f32_e32 v60, 0xbfb8aa3b, v43
	v_exp_f32_e32 v61, v61
	v_exp_f32_e32 v52, v52
	v_exp_f32_e32 v53, v53
	v_exp_f32_e32 v54, v54
	v_exp_f32_e32 v55, v55
	v_exp_f32_e32 v56, v56
	v_exp_f32_e32 v57, v57
	v_exp_f32_e32 v60, v60
	v_add_f32_e32 v61, 1.0, v61
	v_add_f32_e32 v52, 1.0, v52
	v_add_f32_e32 v53, 1.0, v53
	v_add_f32_e32 v54, 1.0, v54
	v_add_f32_e32 v55, 1.0, v55
	v_add_f32_e32 v56, 1.0, v56
	v_add_f32_e32 v57, 1.0, v57
	v_add_f32_e32 v60, 1.0, v60
	v_rcp_f32_e32 v61, v61
	v_rcp_f32_e32 v52, v52
	v_rcp_f32_e32 v53, v53
	v_rcp_f32_e32 v54, v54
	v_rcp_f32_e32 v55, v55
	v_rcp_f32_e32 v56, v56
	v_rcp_f32_e32 v57, v57
	v_rcp_f32_e32 v60, v60
	v_mul_f32_e32 v37, v37, v61
	v_mul_f32_e32 v51, v51, v52
	v_mul_f32_e32 v39, v39, v53
	v_mul_f32_e32 v47, v47, v54
	v_mul_f32_e32 v41, v41, v55
	v_mul_f32_e32 v49, v49, v56
	v_mul_f32_e32 v35, v35, v57
	v_mul_f32_e32 v43, v43, v60
	v_mul_f32_e32 v37, v36, v37
	v_mul_f32_e32 v50, v50, v51
	v_mul_f32_e32 v38, v38, v39
	v_mul_f32_e32 v39, v46, v47
	v_mul_f32_e32 v40, v40, v41
	v_mul_f32_e32 v41, v48, v49
	v_mul_f32_e32 v46, v34, v35
	v_mul_f32_e32 v42, v42, v43
	v_cvt_pk_bf16_f32 v34, v50, v38
	v_cvt_pk_bf16_f32 v35, v39, v40
	v_cvt_pk_bf16_f32 v36, v41, v46
	v_cvt_pk_bf16_f32 v37, v42, v37
	global_store_dwordx4 v[44:45], v[34:37], off
	s_nop 0
	s_nop 0
	v_mov_b32_e32 v34, v30
	v_mov_b32_e32 v30, v32
	v_mov_b32_e32 v32, v26
	v_mov_b32_e32 v26, v28
	v_add_u32_e32 v28, 0xa0, v138
	v_mov_b32_e32 v35, v22
	v_mov_b32_e32 v22, v31
	v_mov_b32_e32 v31, v24
	v_mov_b32_e32 v24, v33
	v_mov_b32_e32 v33, v18
	v_mov_b32_e32 v18, v27
	v_mov_b32_e32 v27, v20
	v_mov_b32_e32 v20, v29
	v_lshrrev_b32_e32 v29, 3, v28
	v_lshlrev_b32_e32 v37, 6, v28
	v_lshlrev_b32_e32 v28, 2, v28
	v_and_or_b32 v29, v29, 12, s61
	v_and_or_b32 v37, v37, s60, v142
	v_and_b32_e32 v28, 32, v28
	v_lshlrev_b32_e32 v29, 10, v29
	v_bitop3_b32 v132, v37, v29, v28 bitop3:0xde
	s_nop 0
	s_nop 1
	s_nop 0
	s_nop 1
	s_nop 1
	s_nop 1
	v_lshl_add_u64 v[28:29], v[58:59], 0, v[132:133]
	v_mov_b32_e32 v36, v238
	v_pk_mul_f32 v[20:21], v[20:21], v[36:37] op_sel_hi:[1,0]
	v_pk_mul_f32 v[34:35], v[34:35], v[36:37] op_sel_hi:[1,0]
	v_pk_mul_f32 v[22:23], v[22:23], v[36:37] op_sel_hi:[1,0]
	v_pk_mul_f32 v[30:31], v[30:31], v[36:37] op_sel_hi:[1,0]
	v_pk_mul_f32 v[24:25], v[24:25], v[36:37] op_sel_hi:[1,0]
	v_pk_mul_f32 v[32:33], v[32:33], v[36:37] op_sel_hi:[1,0]
	v_pk_mul_f32 v[18:19], v[18:19], v[36:37] op_sel_hi:[1,0]
	v_pk_mul_f32 v[26:27], v[26:27], v[36:37] op_sel_hi:[1,0]
	v_mul_f32_e32 v43, 0xbfb8aa3b, v21
	v_mul_f32_e32 v36, 0xbfb8aa3b, v35
	v_mul_f32_e32 v37, 0xbfb8aa3b, v23
	v_mul_f32_e32 v38, 0xbfb8aa3b, v31
	v_mul_f32_e32 v39, 0xbfb8aa3b, v25
	v_mul_f32_e32 v40, 0xbfb8aa3b, v33
	v_mul_f32_e32 v41, 0xbfb8aa3b, v19
	v_mul_f32_e32 v42, 0xbfb8aa3b, v27
	v_exp_f32_e32 v43, v43
	v_exp_f32_e32 v36, v36
	v_exp_f32_e32 v37, v37
	v_exp_f32_e32 v38, v38
	v_exp_f32_e32 v39, v39
	v_exp_f32_e32 v40, v40
	v_exp_f32_e32 v41, v41
	v_exp_f32_e32 v42, v42
	v_add_f32_e32 v43, 1.0, v43
	v_add_f32_e32 v36, 1.0, v36
	v_add_f32_e32 v37, 1.0, v37
	v_add_f32_e32 v38, 1.0, v38
	v_add_f32_e32 v39, 1.0, v39
	v_add_f32_e32 v40, 1.0, v40
	v_add_f32_e32 v41, 1.0, v41
	v_add_f32_e32 v42, 1.0, v42
	v_rcp_f32_e32 v43, v43
	v_rcp_f32_e32 v36, v36
	v_rcp_f32_e32 v37, v37
	v_rcp_f32_e32 v38, v38
	v_rcp_f32_e32 v39, v39
; __host__ __device__ __forceinline__ size_t img_off(int row, int col, int nkt) { return ((size_t)((row >> 7) * nkt + (col >> 6)) << 14) + (size_t)lds_byte(row & 127, col & 63); }
; __device__ __forceinline__ unsigned cvt_pk_bf16(float lo, float hi) { unsigned r; asm volatile("v_cvt_pk_bf16_f32 %0, %1, %2" : "=v"(r) : "v"(lo), "v"(hi)); return r; }
; __device__ __forceinline__ float silu_f(float x) { return x * fast_rcp(1.0f + fast_exp2(-1.4426950408889634f * x)); }
;     __device__ __forceinline__ void operator()(const f32x4 (&acc)[2][2][4][2], const Unit& u, int wr, int wc, int fr, int fq) const {
;     ...
;             for (int m = 0; m < 4; ++m) { const int row = row0 + ai * HALF + m * 16;
;                 const float r = 1.0f / sqrtf(__hip_atomic_load(ss + row, __ATOMIC_RELAXED, __HIP_MEMORY_SCOPE_AGENT) * (1.0f / 1024.0f) + 1e-6f);
;                 float a[8];
; #pragma unroll
;                 for (int n = 0; n < 2; ++n)
; #pragma unroll
;                     for (int j = 0; j < 4; ++j) a[4 * n + j] = silu_f(acc[ai][0][m][n][j] * r) * (acc[ai][1][m][n][j] * r);
;                 u32x4 w; w.x = cvt_pk_bf16(a[0], a[1]); w.y = cvt_pk_bf16(a[2], a[3]); w.z = cvt_pk_bf16(a[4], a[5]); w.w = cvt_pk_bf16(a[6], a[7]);
;                 *(u32x4*)((char*)H + img_off(row, col0, 44)) = w; }
	v_rcp_f32_e32 v40, v40
	v_rcp_f32_e32 v41, v41
	v_rcp_f32_e32 v42, v42
	v_mul_f32_e32 v21, v21, v43
	v_mul_f32_e32 v35, v35, v36
	v_mul_f32_e32 v23, v23, v37
	v_mul_f32_e32 v31, v31, v38
	v_mul_f32_e32 v25, v25, v39
	v_mul_f32_e32 v33, v33, v40
	v_mul_f32_e32 v19, v19, v41
	v_mul_f32_e32 v27, v27, v42
	v_mul_f32_e32 v21, v20, v21
	v_mul_f32_e32 v34, v34, v35
	v_mul_f32_e32 v22, v22, v23
	v_mul_f32_e32 v23, v30, v31
	v_mul_f32_e32 v24, v24, v25
	v_mul_f32_e32 v25, v32, v33
	v_mul_f32_e32 v30, v18, v19
	v_mul_f32_e32 v26, v26, v27
	v_cvt_pk_bf16_f32 v18, v34, v22
	v_cvt_pk_bf16_f32 v19, v23, v24
	v_cvt_pk_bf16_f32 v20, v25, v30
	v_cvt_pk_bf16_f32 v21, v26, v21
	global_store_dwordx4 v[28:29], v[18:21], off
	s_nop 0
	s_nop 0
	v_mov_b32_e32 v18, v14
	v_mov_b32_e32 v14, v16
	v_mov_b32_e32 v16, v10
	v_mov_b32_e32 v10, v12
	v_add_u32_e32 v12, 0xb0, v138
	v_mov_b32_e32 v19, v6
	v_mov_b32_e32 v6, v15
	v_mov_b32_e32 v15, v8
	v_mov_b32_e32 v8, v17
	v_mov_b32_e32 v17, v2
	v_mov_b32_e32 v2, v11
	v_mov_b32_e32 v11, v4
	v_mov_b32_e32 v4, v13
	v_lshrrev_b32_e32 v13, 3, v12
	v_lshlrev_b32_e32 v21, 6, v12
	v_lshlrev_b32_e32 v12, 2, v12
	v_and_or_b32 v13, v13, 14, s61
	v_and_or_b32 v21, v21, s60, v142
	v_and_b32_e32 v12, 32, v12
	v_lshlrev_b32_e32 v13, 10, v13
	v_bitop3_b32 v132, v21, v13, v12 bitop3:0xde
	s_nop 0
	s_nop 1
	s_nop 0
	s_nop 1
	s_nop 1
	s_nop 1
	v_lshl_add_u64 v[12:13], v[58:59], 0, v[132:133]
	v_mov_b32_e32 v20, v239
	v_pk_mul_f32 v[4:5], v[4:5], v[20:21] op_sel_hi:[1,0]
	v_pk_mul_f32 v[18:19], v[18:19], v[20:21] op_sel_hi:[1,0]
	v_pk_mul_f32 v[6:7], v[6:7], v[20:21] op_sel_hi:[1,0]
	v_pk_mul_f32 v[14:15], v[14:15], v[20:21] op_sel_hi:[1,0]
	v_pk_mul_f32 v[8:9], v[8:9], v[20:21] op_sel_hi:[1,0]
	v_pk_mul_f32 v[16:17], v[16:17], v[20:21] op_sel_hi:[1,0]
	v_pk_mul_f32 v[2:3], v[2:3], v[20:21] op_sel_hi:[1,0]
	v_pk_mul_f32 v[10:11], v[10:11], v[20:21] op_sel_hi:[1,0]
	v_mul_f32_e32 v27, 0xbfb8aa3b, v5
	v_mul_f32_e32 v20, 0xbfb8aa3b, v19
	v_mul_f32_e32 v21, 0xbfb8aa3b, v7
	v_mul_f32_e32 v22, 0xbfb8aa3b, v15
	v_mul_f32_e32 v23, 0xbfb8aa3b, v9
	v_mul_f32_e32 v24, 0xbfb8aa3b, v17
	v_mul_f32_e32 v25, 0xbfb8aa3b, v3
	v_mul_f32_e32 v26, 0xbfb8aa3b, v11
	v_exp_f32_e32 v27, v27
	v_exp_f32_e32 v20, v20
	v_exp_f32_e32 v21, v21
	v_exp_f32_e32 v22, v22
	v_exp_f32_e32 v23, v23
	v_exp_f32_e32 v24, v24
	v_exp_f32_e32 v25, v25
	v_exp_f32_e32 v26, v26
	v_add_f32_e32 v27, 1.0, v27
	v_add_f32_e32 v20, 1.0, v20
	v_add_f32_e32 v21, 1.0, v21
	v_add_f32_e32 v22, 1.0, v22
	v_add_f32_e32 v23, 1.0, v23
	v_add_f32_e32 v24, 1.0, v24
	v_add_f32_e32 v25, 1.0, v25
	v_add_f32_e32 v26, 1.0, v26
	v_rcp_f32_e32 v27, v27
	v_rcp_f32_e32 v20, v20
	v_rcp_f32_e32 v21, v21
	v_rcp_f32_e32 v22, v22
	v_rcp_f32_e32 v23, v23
	v_rcp_f32_e32 v24, v24
	v_rcp_f32_e32 v25, v25
	v_rcp_f32_e32 v26, v26
	v_mul_f32_e32 v5, v5, v27
	s_andn2_b64 vcc, exec, s[2:3]
	v_mul_f32_e32 v19, v19, v20
	v_mul_f32_e32 v7, v7, v21
	v_mul_f32_e32 v15, v15, v22
	v_mul_f32_e32 v9, v9, v23
	v_mul_f32_e32 v17, v17, v24
	v_mul_f32_e32 v3, v3, v25
	v_mul_f32_e32 v11, v11, v26
	v_mul_f32_e32 v5, v4, v5
	s_mov_b64 s[2:3], -1
	v_mul_f32_e32 v18, v18, v19
	v_mul_f32_e32 v6, v6, v7
	v_mul_f32_e32 v7, v14, v15
	v_mul_f32_e32 v8, v8, v9
	v_mul_f32_e32 v9, v16, v17
	v_mul_f32_e32 v14, v2, v3
	v_mul_f32_e32 v10, v10, v11
	v_cvt_pk_bf16_f32 v2, v18, v6
	v_cvt_pk_bf16_f32 v3, v7, v8
	v_cvt_pk_bf16_f32 v4, v9, v14
	v_cvt_pk_bf16_f32 v5, v10, v5
	global_store_dwordx4 v[12:13], v[2:5], off
	s_cbranch_vccnz .LBB0_973
	s_andn2_b64 vcc, exec, s[16:17]
	s_cbranch_vccnz .LBB0_972
	s_barrier
	s_branch .LBB0_972
